# split-phase barrier at the GLU->gate GEMM seam (XCC-local mode): arrive, run the first gate-GEMM K-loop, wait for the release just before its merge epilogue
# speedup vs baseline: 1.0052x; 1.0052x over previous
; __device__ __forceinline__ unsigned xb_ld(unsigned* p)              { return __hip_atomic_load(p, __ATOMIC_RELAXED, __HIP_MEMORY_SCOPE_AGENT); }
; __device__ __forceinline__ unsigned xb_add(unsigned* p, unsigned v) { return __hip_atomic_fetch_add(p, v, __ATOMIC_RELAXED, __HIP_MEMORY_SCOPE_AGENT); }
; #define XB_SPIN(cond, bar) do { unsigned _sp = 0; while (cond) { __builtin_amdgcn_s_sleep(1); \
;     if ((++_sp & 255u) == 0u) { if (xb_ld(&(bar)[XB_TMO])) break; if (_sp > XB_SPIN_CAP) { atomicAdd(&(bar)[XB_TMO], 1u); break; } } } } while (0)
; __device__ __forceinline__ void xcd_barrier(const XcdBarrier& b) {
;     asm volatile("s_waitcnt vmcnt(0)" ::: "memory");
;     __syncthreads();
;     if (threadIdx.x == 0) {
;         unsigned* bar = b.bar;
;         __builtin_amdgcn_s_waitcnt(0);
;         unsigned nloc = b.st[0], nx = b.st[1];
;         if (nloc == 0u) { xcd_barrier_complete(bar, b.x, nloc, nx); b.st[0] = nloc; b.st[1] = nx; }
;         const unsigned old = xb_add(&bar[XB_XSUB(b.x)], 1u);
;         const unsigned gen = old / nloc;
;         if (old + 1u == (gen + 1u) * nloc) {
;             __builtin_amdgcn_fence(__ATOMIC_RELEASE, "agent");
;             asm volatile("s_waitcnt vmcnt(0)" ::: "memory");
;             const unsigned og = xb_add(&bar[XB_TOP], 1u);
;             const unsigned tg = og / nx;
;             if (og + 1u == (tg + 1u) * nx) xb_add(&bar[XB_TOPGEN], 1u);
;             else XB_SPIN(xb_ld(&bar[XB_TOPGEN]) == tg, bar);
;             __builtin_amdgcn_fence(__ATOMIC_ACQUIRE, "agent");
;             xb_add(&bar[XB_XGEN(b.x)], 1u);
;             asm volatile("s_waitcnt vmcnt(0)" ::: "memory");
;         } else {
;             XB_SPIN(xb_ld(&bar[XB_XGEN(b.x)]) == gen, bar);
;             __builtin_amdgcn_fence(__ATOMIC_ACQUIRE, "agent");
;             asm volatile("s_waitcnt vmcnt(0)" ::: "memory");
;         }
.LBB0_435:
	s_waitcnt vmcnt(0)
	s_waitcnt vmcnt(0) lgkmcnt(0)
	s_barrier
	s_and_saveexec_b64 s[4:5], s[90:91]
	s_cbranch_execz .LBB0_487
	s_cmp_eq_u32 s101, 1
	s_cbranch_scc0 .Lsp5_full
	buffer_inv sc1
	v_mov_b32_e32 v0, 0x23f20
	ds_read_b32 v2, v0
	s_lshl_b32 s6, s3, 8
	s_add_u32 s6, s94, s6
	s_addc_u32 s7, s95, 0
	v_mov_b32_e32 v3, 0x1000
	v_mov_b32_e32 v4, 1
	global_atomic_add v3, v3, v4, s[6:7] offset:1024 sc0
	s_waitcnt vmcnt(0) lgkmcnt(0)
	v_mul_u32_u24_e32 v2, 5, v2
	v_add_u32_e32 v3, 1, v3
	v_cmp_eq_u32_e32 vcc, v3, v2
	s_and_saveexec_b64 s[8:9], vcc
	s_cbranch_execz .LBB0_487
	v_mov_b32_e32 v0, 0x2000
	v_mov_b32_e32 v1, 1
	global_atomic_add v0, v1, s[6:7] offset:1024
	s_branch .LBB0_487
.Lsp5_full:
	s_add_i32 s6, 0, 0x23f20
	v_mov_b32_e32 v0, s6
	s_waitcnt vmcnt(0) expcnt(0) lgkmcnt(0)
	ds_read_b32 v2, v0
	s_add_i32 s6, 0, 0x23f24
	v_mov_b32_e32 v0, s6
	ds_read_b32 v0, v0
	s_waitcnt lgkmcnt(1)
	v_cmp_ne_u32_e32 vcc, 0, v2
	s_cbranch_vccnz .LBB0_451
	s_add_u32 s6, s58, 0xc0200
	s_addc_u32 s7, s59, 0
	s_add_u32 s8, s58, 0xc0400
	s_addc_u32 s9, s59, 0
	s_add_u32 s12, s58, 0xc0500
	s_addc_u32 s13, s59, 0
	s_add_u32 s14, s58, 0xc0600
	s_addc_u32 s15, s59, 0
	s_add_u32 s16, s58, 0xc0700
	s_addc_u32 s17, s59, 0
	s_add_u32 s18, s58, 0xc0800
	s_addc_u32 s19, s59, 0
	s_add_u32 s20, s58, 0xc0900
	s_addc_u32 s21, s59, 0
	s_add_u32 s22, s58, 0xc0a00
	s_addc_u32 s23, s59, 0
	s_add_u32 s24, s58, 0xc0b00
	s_addc_u32 s25, s59, 0
	s_add_u32 s26, s58, 0xc0c00
	s_addc_u32 s27, s59, 0
	s_add_u32 s28, s58, 0xc0d00
	s_addc_u32 s29, s59, 0
	s_add_u32 s30, s58, 0xc0e00
	s_addc_u32 s31, s59, 0
	s_add_u32 s34, s58, 0xc0f00
	s_addc_u32 s35, s59, 0
	s_add_u32 s36, s58, 0xc1000
	s_addc_u32 s37, s59, 0
	s_add_u32 s38, s58, 0xc1100
	s_addc_u32 s39, s59, 0
	s_add_u32 s42, s58, 0xc1200
	s_addc_u32 s43, s59, 0
	s_mul_i32 s33, s93, s97
	s_add_u32 s62, s58, 0xc1300
	s_mul_i32 s33, s33, s92
	s_addc_u32 s63, s59, 0
	s_mov_b32 s40, 1
	v_mov_b32_e32 v16, 0
	s_branch .LBB0_439

;     __host__ __device__ bool next(int i, Unit& u) const {
;         const long L = (long)i * G + c; if (L >= nwg) return false;
;         int wgid = (int)L; { const int q = nwg / NXCD, r = nwg % NXCD, xcd = wgid % NXCD, off = wgid / NXCD; wgid = (xcd < r ? xcd * (q + 1) : r * (q + 1) + (xcd - r) * q) + off; }
;         const int nig = WGM * nN, gid = wgid / nig, fm = gid * WGM, gsz = (nM - fm) < WGM ? (nM - fm) : WGM;
;         u.pm = fm + ((wgid % nig) % gsz); u.pn = (wgid % nig) / gsz; return true;
; __device__ __forceinline__ void xcd_barrier(const XcdBarrier& b) {
;     ...
;     __syncthreads();
; }
.LBB0_487:
	s_or_b64 exec, exec, s[4:5]
	s_mov_b32 s99, s101
	s_add_u32 s8, s58, 0x19400000
	s_addc_u32 s9, s59, 0
	s_and_b64 vcc, exec, s[0:1]
	v_readfirstlane_b32 s12, v224
	s_waitcnt lgkmcnt(0)
	s_barrier
	s_cbranch_vccnz .LBB0_511
	s_ashr_i32 s33, s2, 31
	s_lshr_b32 s0, s33, 29
	s_add_i32 s4, s2, s0
	s_and_b32 s0, s4, -8
	s_sub_i32 s6, s2, s0
	s_cmp_gt_i32 s6, -1
	s_cbranch_scc0 .LBB0_490
	s_lshl_b32 s5, s6, 7
	s_cbranch_execz .LBB0_491
	s_branch .LBB0_492

; #define PG8_BAR __builtin_amdgcn_s_barrier()
; template <class Epi, class Sched, bool ALIGN_EPI = false, bool SP2 = false, bool F16 = false>
; __device__ __forceinline__ void gemm_phase(PG8_LAS unsigned char* lds, const Gemm g, const Sched& S, const Epi& E) {
;     ...
;         if constexpr (ALIGN_EPI) { if (wr == 0) PG8_BAR; }
;         if constexpr (!Epi::AFTER_DRAIN) { E(acc, cur, wr, wc, fr, fq); S.done(cur); }
.LBB0_507:
	s_cmp_eq_u32 s99, 1
	s_cbranch_scc0 .Lsp5_nowait
	s_mov_b32 s99, 0
	s_and_saveexec_b64 s[72:73], s[90:91]
	s_cbranch_execz .Lsp5_wdone
	s_lshl_b32 s74, s3, 8
	s_add_u32 s74, s94, s74
	s_addc_u32 s75, s95, 0
	v_mov_b32_e32 v182, 0x2000
	s_mov_b32 s70, 0
.Lsp5_poll:
	global_load_dword v183, v182, s[74:75] offset:1024 sc1
	s_waitcnt vmcnt(0)
	v_cmp_gt_u32_e32 vcc, 5, v183
	s_cbranch_vccz .Lsp5_wdone
	s_add_i32 s70, s70, 1
	s_cmp_lt_u32 s70, 0x40000
	s_cbranch_scc0 .Lsp5_wdone
	s_sleep 1
	s_branch .Lsp5_poll
.Lsp5_wdone:
	s_or_b64 exec, exec, s[72:73]
	s_barrier
